# attention loop: K-fragment reads hoisted, row-sum adds interleaved under the QK MFMAs (2nd half), first PV operand prefetched into free VGPRs (both halves); bit-identical
# baseline (speedup 1.0000x reference)
.LBB0_694:
	ds_read_b128 v[80:83], v196 offset:28672
	ds_read_b128 v[76:79], v194 offset:28672
	ds_read_b128 v[146:149], v194 offset:34816
	ds_read_b128 v[150:153], v196 offset:34816
	ds_read_b128 v[164:167], v198 offset:28672
	ds_read_b128 v[204:207], v198 offset:34816
	ds_read_b128 v[168:171], v199 offset:28672
	ds_read_b128 v[208:211], v199 offset:34816
	ds_read_b128 v[212:215], v201 offset:28672
	ds_read_b128 v[220:223], v201 offset:34816
	s_waitcnt lgkmcnt(8)
	v_mfma_scale_f32_32x32x64_f8f6f4 v[82:97], v[76:83], v[114:121], 0, v1, v1 op_sel_hi:[0,0,0]
	v_exp_f32_e32 v129, v70
	v_exp_f32_e32 v174, v71
	v_exp_f32_e32 v175, v68
	v_exp_f32_e32 v228, v69
	v_exp_f32_e32 v229, v66
	v_exp_f32_e32 v230, v67
	v_exp_f32_e32 v231, v74
	v_exp_f32_e32 v232, v75
	v_exp_f32_e32 v233, v72
	v_exp_f32_e32 v234, v73
	v_exp_f32_e32 v124, v124
	v_exp_f32_e32 v125, v125
	v_exp_f32_e32 v122, v122
	ds_read_b128 v[216:219], v200 offset:28672
	ds_read_b128 v[224:227], v200 offset:34816
	ds_read_b128 v[244:247], v189
	ds_read_b128 v[248:251], v190
	v_exp_f32_e32 v123, v123
	s_waitcnt lgkmcnt(10)
	v_mfma_scale_f32_32x32x64_f8f6f4 v[66:81], v[146:153], v[114:121], 0, v1, v1 op_sel_hi:[0,0,0]
	v_add_f32_e32 v146, 0, v144
	v_add_f32_e32 v146, v145, v146
	v_add_f32_e32 v146, v136, v146
	v_add_f32_e32 v146, v138, v146
	v_add_f32_e32 v146, v142, v146
	v_add_f32_e32 v146, v143, v146
	v_add_f32_e32 v146, v140, v146
	v_add_f32_e32 v146, v141, v146
	v_add_f32_e32 v146, v137, v146
	v_add_f32_e32 v146, v139, v146
	v_add_f32_e32 v146, v130, v146
	v_add_f32_e32 v146, v131, v146
	v_add_f32_e32 v146, v134, v146
	v_add_f32_e32 v146, v135, v146
	v_add_f32_e32 v146, v132, v146
	s_waitcnt lgkmcnt(7)
	v_mfma_scale_f32_32x32x64_f8f6f4 v[82:97], v[164:171], v[106:113], v[82:97], v1, v1 op_sel_hi:[0,0,0]
	v_add_f32_e32 v146, v133, v146
	v_add_f32_e32 v146, v124, v146
	v_add_f32_e32 v146, v125, v146
	v_add_f32_e32 v146, v122, v146
	v_add_f32_e32 v146, v123, v146
	v_add_f32_e32 v146, v129, v146
	v_add_f32_e32 v146, v174, v146
	v_add_f32_e32 v146, v175, v146
	v_add_f32_e32 v146, v228, v146
	v_add_f32_e32 v146, v229, v146
	v_add_f32_e32 v146, v230, v146
	v_exp_f32_e32 v126, v126
	v_add_f32_e32 v146, v231, v146
	v_exp_f32_e32 v127, v127
	v_add_f32_e32 v146, v232, v146
	s_waitcnt lgkmcnt(6)
	v_mfma_scale_f32_32x32x64_f8f6f4 v[66:81], v[204:211], v[106:113], v[66:81], v1, v1 op_sel_hi:[0,0,0]
	v_add_f32_e32 v146, v233, v146
	v_add_f32_e32 v146, v234, v146
	v_add_f32_e32 v146, v126, v146
	v_add_f32_e32 v203, v127, v146
	v_mov_b32_e32 v146, 0
	v_mov_b32_e32 v150, 0
	v_mov_b32_e32 v147, 0
	v_mov_b32_e32 v151, 0
	v_mov_b32_e32 v148, 0
	v_mov_b32_e32 v152, 0
	v_mov_b32_e32 v149, 0
	v_mov_b32_e32 v153, 0
	v_cvt_pk_fp8_f32 v146, v144, v145
	v_cvt_pk_fp8_f32 v150, v124, v125
	v_cvt_pk_fp8_f32 v147, v142, v143
	s_waitcnt lgkmcnt(3)
	v_mfma_scale_f32_32x32x64_f8f6f4 v[82:97], v[212:219], v[98:105], v[82:97], v1, v1 op_sel_hi:[0,0,0]
	v_cvt_pk_fp8_f32 v151, v129, v174
	v_cvt_pk_fp8_f32 v148, v137, v139
	v_cvt_pk_fp8_f32 v152, v229, v230
	v_cvt_pk_fp8_f32 v149, v134, v135
	v_cvt_pk_fp8_f32 v153, v233, v234
	v_mov_b32_e32 v204, v203
	s_nop 1
	v_permlane32_swap_b32_e32 v203, v204
	v_cvt_pk_fp8_f32 v146, v136, v138 op_sel:[0,0,1]
	v_cvt_pk_fp8_f32 v150, v122, v123 op_sel:[0,0,1]
	v_cvt_pk_fp8_f32 v147, v140, v141 op_sel:[0,0,1]
	v_cvt_pk_fp8_f32 v151, v175, v228 op_sel:[0,0,1]
	v_cvt_pk_fp8_f32 v148, v130, v131 op_sel:[0,0,1]
	v_cvt_pk_fp8_f32 v152, v231, v232 op_sel:[0,0,1]
	v_cvt_pk_fp8_f32 v149, v132, v133 op_sel:[0,0,1]
	s_waitcnt lgkmcnt(2)
	v_mfma_scale_f32_32x32x64_f8f6f4 v[66:81], v[220:227], v[98:105], v[66:81], v1, v1 op_sel_hi:[0,0,0]
	v_cvt_pk_fp8_f32 v153, v126, v127 op_sel:[0,0,1]
	s_add_i32 s8, s11, 0xffffe000
	s_add_i32 s9, s72, 0xffffd000
	buffer_load_dwordx4 v[164:167], v191, s[40:43], s8 offen
	buffer_load_dwordx4 v[168:171], v191, s[36:39], s9 offen
	buffer_load_dwordx2 v[174:175], v192, s[36:39], s9 offen
	v_max_f32_e32 v122, v83, v83
	v_max_f32_e32 v123, v82, v82
	v_max_f32_e32 v122, v123, v122
	v_max3_f32 v122, v122, v84, v85
	v_max3_f32 v122, v122, v86, v87
	v_max3_f32 v122, v122, v88, v89
	v_max3_f32 v122, v122, v90, v91
	ds_read_b128 v[138:141], v187 offset:2048
	ds_read_b128 v[206:209], v187 offset:4096
	v_max3_f32 v122, v122, v92, v93
	v_max3_f32 v122, v122, v94, v95
	v_max3_f32 v122, v122, v96, v97
	s_waitcnt lgkmcnt(2)
	v_mfma_scale_f32_32x32x64_f8f6f4 v[2:17], v[146:153], v[244:251], v[2:17], v1, v1 op_sel_hi:[0,0,0]
	ds_read_b128 v[142:145], v186 offset:2048
	ds_read_b128 v[130:133], v187 offset:6144
	ds_read_b128 v[210:213], v186 offset:4096
	ds_read_b128 v[134:137], v186 offset:6144
	v_max3_f32 v122, v122, v66, v67
	v_max3_f32 v122, v122, v68, v69
	v_max3_f32 v122, v122, v70, v71
	v_max3_f32 v122, v122, v72, v73
	v_max3_f32 v122, v122, v74, v75
	v_max3_f32 v122, v122, v76, v77
	v_max3_f32 v122, v122, v78, v79
	v_max3_f32 v122, v122, v80, v81
	v_mov_b32_e32 v123, v122
	s_nop 1
	v_permlane32_swap_b32_e32 v122, v123
	v_max_f32_e32 v123, v123, v123
	v_max_f32_e32 v122, v122, v122
	v_max_f32_e32 v122, v122, v123
	s_waitcnt lgkmcnt(3)
	v_mfma_scale_f32_32x32x64_f8f6f4 v[50:65], v[146:153], v[138:145], v[50:65], v1, v1 op_sel_hi:[0,0,0]
	v_max_f32_e32 v124, v128, v128
	v_sub_f32_e32 v123, v122, v128
	v_max_f32_e32 v122, v124, v122
	v_sub_f32_e32 v124, v128, v122
	v_mul_f32_e32 v124, 0x3dd53b94, v124
	v_exp_f32_e32 v124, v124
	v_cmp_ge_f32_e32 vcc, s61, v123
	s_cmp_eq_u64 vcc, exec
	s_cselect_b64 s[8:9], -1, 0
	s_waitcnt lgkmcnt(0)
	s_barrier
	s_waitcnt vmcnt(3)
	v_cndmask_b32_e64 v205, v124, 1.0, s[8:9]
	v_cmp_gt_f32_e32 vcc, 1.0, v205
	v_mfma_scale_f32_32x32x64_f8f6f4 v[34:49], v[146:153], v[206:213], v[34:49], v1, v1 op_sel_hi:[0,0,0]
	s_waitcnt vmcnt(3)
	ds_write_b128 v193, v[156:159]
	ds_write_b128 v195, v[160:163] offset:16384
	ds_write_b64 v197, v[172:173] offset:16384
	v_mfma_scale_f32_32x32x64_f8f6f4 v[18:33], v[146:153], v[130:137], v[18:33], v1, v1 op_sel_hi:[0,0,0]
	s_cbranch_vccz .LBB0_698
	s_and_saveexec_b64 s[56:57], s[6:7]
	ds_write_b32 v185, v205 offset:41088
	s_or_b64 exec, exec, s[56:57]
	s_waitcnt lgkmcnt(0)
	v_add_u32_e32 v123, v183, v184
	ds_read_b128 v[124:127], v123 offset:41184
	ds_read_b128 v[130:133], v123 offset:41152
	ds_read_b128 v[134:137], v123 offset:41120
	ds_read_b128 v[138:141], v123 offset:41088
	s_waitcnt lgkmcnt(3)
	v_pk_mul_f32 v[14:15], v[14:15], v[124:125]
	s_waitcnt lgkmcnt(2)
	v_pk_mul_f32 v[10:11], v[10:11], v[130:131]
	s_waitcnt lgkmcnt(1)
	v_pk_mul_f32 v[6:7], v[6:7], v[134:135]
	v_pk_mul_f32 v[16:17], v[16:17], v[126:127]
	v_pk_mul_f32 v[12:13], v[12:13], v[132:133]
	v_pk_mul_f32 v[8:9], v[8:9], v[136:137]
	s_waitcnt lgkmcnt(0)
	v_pk_mul_f32 v[4:5], v[4:5], v[140:141]
	v_pk_mul_f32 v[2:3], v[2:3], v[138:139]
	v_pk_mul_f32 v[62:63], v[62:63], v[124:125]
	v_pk_mul_f32 v[58:59], v[58:59], v[130:131]
	v_pk_mul_f32 v[54:55], v[54:55], v[134:135]
	v_pk_mul_f32 v[64:65], v[64:65], v[126:127]
	v_pk_mul_f32 v[60:61], v[60:61], v[132:133]
	v_pk_mul_f32 v[56:57], v[56:57], v[136:137]
	v_pk_mul_f32 v[52:53], v[52:53], v[140:141]
	v_pk_mul_f32 v[50:51], v[50:51], v[138:139]
	v_pk_mul_f32 v[46:47], v[46:47], v[124:125]
	v_pk_mul_f32 v[42:43], v[42:43], v[130:131]
	v_pk_mul_f32 v[38:39], v[38:39], v[134:135]
	v_pk_mul_f32 v[48:49], v[48:49], v[126:127]
	v_pk_mul_f32 v[44:45], v[44:45], v[132:133]
	v_pk_mul_f32 v[40:41], v[40:41], v[136:137]
	v_pk_mul_f32 v[36:37], v[36:37], v[140:141]
	v_pk_mul_f32 v[34:35], v[34:35], v[138:139]
	v_pk_mul_f32 v[30:31], v[30:31], v[124:125]
	v_pk_mul_f32 v[26:27], v[26:27], v[130:131]
	v_pk_mul_f32 v[22:23], v[22:23], v[134:135]
	v_pk_mul_f32 v[32:33], v[32:33], v[126:127]
	v_pk_mul_f32 v[28:29], v[28:29], v[132:133]
	v_pk_mul_f32 v[24:25], v[24:25], v[136:137]
	v_pk_mul_f32 v[20:21], v[20:21], v[140:141]
	v_pk_mul_f32 v[18:19], v[18:19], v[138:139]
.LBB0_698:
	v_cndmask_b32_e64 v206, v122, v128, s[8:9]
	v_fma_f32 v207, v206, s62, 4.0
	v_fmamk_f32 v122, v82, 0x3dd53b94, v207
	v_fmamk_f32 v123, v83, 0x3dd53b94, v207
	v_fmamk_f32 v124, v84, 0x3dd53b94, v207
	v_fmamk_f32 v125, v85, 0x3dd53b94, v207
	v_fmamk_f32 v126, v86, 0x3dd53b94, v207
	v_fmamk_f32 v127, v87, 0x3dd53b94, v207
	v_fmamk_f32 v128, v88, 0x3dd53b94, v207
	v_fmamk_f32 v129, v89, 0x3dd53b94, v207
	v_fmamk_f32 v130, v90, 0x3dd53b94, v207
	v_fmamk_f32 v131, v91, 0x3dd53b94, v207
	v_fmamk_f32 v132, v92, 0x3dd53b94, v207
	v_fmamk_f32 v133, v93, 0x3dd53b94, v207
	v_fmamk_f32 v134, v94, 0x3dd53b94, v207
	v_fmamk_f32 v95, v95, 0x3dd53b94, v207
	v_fmamk_f32 v96, v96, 0x3dd53b94, v207
	v_fmamk_f32 v97, v97, 0x3dd53b94, v207
	v_exp_f32_e32 v223, v122
	v_exp_f32_e32 v224, v123
	v_exp_f32_e32 v215, v124
	v_exp_f32_e32 v217, v125
	v_exp_f32_e32 v221, v126
	v_exp_f32_e32 v222, v127
	v_exp_f32_e32 v219, v128
	v_exp_f32_e32 v220, v129
	v_exp_f32_e32 v216, v130
	v_exp_f32_e32 v218, v131
	v_exp_f32_e32 v209, v132
	v_exp_f32_e32 v210, v133
	v_exp_f32_e32 v213, v134
	v_exp_f32_e32 v214, v95
	v_exp_f32_e32 v211, v96
	v_exp_f32_e32 v212, v97
	v_fmamk_f32 v82, v66, 0x3dd53b94, v207
	v_fmamk_f32 v83, v67, 0x3dd53b94, v207
	v_fmamk_f32 v84, v68, 0x3dd53b94, v207
	v_fmamk_f32 v85, v69, 0x3dd53b94, v207
	v_fmamk_f32 v86, v70, 0x3dd53b94, v207
	v_fmamk_f32 v87, v71, 0x3dd53b94, v207
	v_fmamk_f32 v88, v72, 0x3dd53b94, v207
	v_fmamk_f32 v89, v73, 0x3dd53b94, v207
	v_fmamk_f32 v90, v74, 0x3dd53b94, v207
	v_fmamk_f32 v91, v75, 0x3dd53b94, v207
	v_fmamk_f32 v92, v76, 0x3dd53b94, v207
	v_fmamk_f32 v93, v77, 0x3dd53b94, v207
	v_fmamk_f32 v94, v78, 0x3dd53b94, v207
	v_fmamk_f32 v95, v79, 0x3dd53b94, v207
	v_fmamk_f32 v96, v80, 0x3dd53b94, v207
	v_fmac_f32_e32 v207, 0x3dd53b94, v81
	s_waitcnt lgkmcnt(0)
	s_barrier
	ds_read_b128 v[66:69], v194 offset:16384
	ds_read_b128 v[74:77], v194 offset:22528
	ds_read_b128 v[70:73], v196 offset:16384
	ds_read_b128 v[78:81], v196 offset:22528
	ds_read_b128 v[146:149], v198 offset:16384
	ds_read_b128 v[138:141], v198 offset:22528
	ds_read_b128 v[150:153], v199 offset:16384
	ds_read_b128 v[142:145], v199 offset:22528
	ds_read_b128 v[130:133], v201 offset:16384
	ds_read_b128 v[122:125], v201 offset:22528
	ds_read_b128 v[134:137], v200 offset:16384
	ds_read_b128 v[126:129], v200 offset:22528
	ds_read_b128 v[244:247], v189 offset:8192
	ds_read_b128 v[248:251], v190 offset:8192
	v_exp_f32_e32 v239, v82
	v_exp_f32_e32 v240, v83
	v_exp_f32_e32 v233, v84
	v_exp_f32_e32 v234, v85
	v_exp_f32_e32 v237, v86
	v_exp_f32_e32 v238, v87
	v_exp_f32_e32 v235, v88
	v_exp_f32_e32 v236, v89
	v_exp_f32_e32 v231, v90
	v_exp_f32_e32 v232, v91
	v_exp_f32_e32 v225, v92
	v_exp_f32_e32 v226, v93
	v_exp_f32_e32 v229, v94
	v_exp_f32_e32 v230, v95
	v_exp_f32_e32 v227, v96
	v_exp_f32_e32 v228, v207
	s_cmpk_gt_u32 s73, 0x80
	s_cselect_b64 s[56:57], -1, 0
	s_and_b64 vcc, exec, s[56:57]
	s_cbranch_vccnz .LBB0_700
	buffer_load_dwordx4 v[156:159], v191, s[40:43], s11 offen
	buffer_load_dwordx4 v[160:163], v191, s[36:39], s72 offen
	buffer_load_dwordx2 v[172:173], v192, s[36:39], s72 offen
.LBB0_700:
	s_waitcnt lgkmcnt(11)
	v_mfma_scale_f32_32x32x64_f8f6f4 v[82:97], v[66:73], v[114:121], 0, v1, v1 op_sel_hi:[0,0,0]
	v_add_f32_e32 v241, 0, v223
	v_add_f32_e32 v241, v224, v241
	v_add_f32_e32 v241, v215, v241
	v_add_f32_e32 v241, v217, v241
	v_add_f32_e32 v241, v221, v241
	v_add_f32_e32 v241, v222, v241
	v_add_f32_e32 v241, v219, v241
	v_add_f32_e32 v241, v220, v241
	s_waitcnt lgkmcnt(10)
	v_mfma_scale_f32_32x32x64_f8f6f4 v[66:81], v[74:81], v[114:121], 0, v1, v1 op_sel_hi:[0,0,0]
	v_add_f32_e32 v241, v216, v241
	v_add_f32_e32 v241, v218, v241
	v_add_f32_e32 v241, v209, v241
	v_add_f32_e32 v241, v210, v241
	v_add_f32_e32 v241, v213, v241
	v_add_f32_e32 v241, v214, v241
	v_add_f32_e32 v241, v211, v241
	v_add_f32_e32 v241, v212, v241
	s_waitcnt lgkmcnt(7)
	v_mfma_scale_f32_32x32x64_f8f6f4 v[82:97], v[146:153], v[106:113], v[82:97], v1, v1 op_sel_hi:[0,0,0]
	v_add_f32_e32 v241, v239, v241
	v_add_f32_e32 v241, v240, v241
	v_add_f32_e32 v241, v233, v241
	v_add_f32_e32 v241, v234, v241
	v_add_f32_e32 v241, v237, v241
	v_add_f32_e32 v241, v238, v241
	v_add_f32_e32 v241, v235, v241
	v_add_f32_e32 v241, v236, v241
	s_waitcnt lgkmcnt(6)
	v_mfma_scale_f32_32x32x64_f8f6f4 v[66:81], v[138:145], v[106:113], v[66:81], v1, v1 op_sel_hi:[0,0,0]
	v_add_f32_e32 v241, v231, v241
	v_add_f32_e32 v241, v232, v241
	v_add_f32_e32 v241, v225, v241
	v_add_f32_e32 v241, v226, v241
	v_add_f32_e32 v241, v229, v241
	v_add_f32_e32 v241, v230, v241
	v_add_f32_e32 v241, v227, v241
	v_add_f32_e32 v207, v228, v241
	v_mov_b32_e32 v208, v207
	v_mov_b32_e32 v138, 0
	v_mov_b32_e32 v142, 0
	v_mov_b32_e32 v139, 0
	v_mov_b32_e32 v143, 0
	v_mov_b32_e32 v140, 0
	v_mov_b32_e32 v144, 0
	v_mov_b32_e32 v141, 0
	v_mov_b32_e32 v145, 0
	v_permlane32_swap_b32_e32 v207, v208
	v_cvt_pk_fp8_f32 v138, v223, v224
	v_cvt_pk_fp8_f32 v142, v239, v240
	v_cvt_pk_fp8_f32 v139, v221, v222
	v_cvt_pk_fp8_f32 v143, v237, v238
	v_cvt_pk_fp8_f32 v140, v216, v218
	v_cvt_pk_fp8_f32 v144, v231, v232
	v_cvt_pk_fp8_f32 v141, v213, v214
	s_waitcnt lgkmcnt(3)
	v_mfma_scale_f32_32x32x64_f8f6f4 v[82:97], v[130:137], v[98:105], v[82:97], v1, v1 op_sel_hi:[0,0,0]
	v_cvt_pk_fp8_f32 v145, v229, v230
	v_cvt_pk_fp8_f32 v138, v215, v217 op_sel:[0,0,1]
	v_cvt_pk_fp8_f32 v142, v233, v234 op_sel:[0,0,1]
	v_cvt_pk_fp8_f32 v139, v219, v220 op_sel:[0,0,1]
	v_cvt_pk_fp8_f32 v143, v235, v236 op_sel:[0,0,1]
	v_cvt_pk_fp8_f32 v140, v209, v210 op_sel:[0,0,1]
	v_cvt_pk_fp8_f32 v144, v225, v226 op_sel:[0,0,1]
	v_cvt_pk_fp8_f32 v141, v211, v212 op_sel:[0,0,1]
	v_cvt_pk_fp8_f32 v145, v227, v228 op_sel:[0,0,1]
	s_waitcnt lgkmcnt(2)
	v_mfma_scale_f32_32x32x64_f8f6f4 v[66:81], v[122:129], v[98:105], v[66:81], v1, v1 op_sel_hi:[0,0,0]
	ds_read_b128 v[130:133], v187 offset:10240
	ds_read_b128 v[146:149], v187 offset:12288
	ds_read_b128 v[134:137], v186 offset:10240
	ds_read_b128 v[210:213], v187 offset:14336
	ds_read_b128 v[150:153], v186 offset:12288
	ds_read_b128 v[214:217], v186 offset:14336
	s_waitcnt lgkmcnt(6)
	v_mfma_scale_f32_32x32x64_f8f6f4 v[2:17], v[138:145], v[244:251], v[2:17], v1, v1 op_sel_hi:[0,0,0]
	s_nop 1
	v_max_f32_e32 v122, v83, v83
	v_max_f32_e32 v123, v82, v82
	v_max_f32_e32 v122, v123, v122
	v_max3_f32 v122, v122, v84, v85
	v_max3_f32 v122, v122, v86, v87
	v_max3_f32 v122, v122, v88, v89
	v_max3_f32 v122, v122, v90, v91
	v_max3_f32 v122, v122, v92, v93
	v_max3_f32 v122, v122, v94, v95
	v_max3_f32 v122, v122, v96, v97
	v_max3_f32 v122, v122, v66, v67
	v_max3_f32 v122, v122, v68, v69
	v_max3_f32 v122, v122, v70, v71
	v_max3_f32 v122, v122, v72, v73
	v_max3_f32 v122, v122, v74, v75
	s_waitcnt lgkmcnt(3)
	v_mfma_scale_f32_32x32x64_f8f6f4 v[50:65], v[138:145], v[130:137], v[50:65], v1, v1 op_sel_hi:[0,0,0]
	v_max3_f32 v122, v122, v76, v77
	v_max3_f32 v122, v122, v78, v79
	v_max3_f32 v122, v122, v80, v81
	v_mov_b32_e32 v123, v122
	s_nop 1
	v_permlane32_swap_b32_e32 v122, v123
	v_max_f32_e32 v123, v123, v123
	v_max_f32_e32 v122, v122, v122
	v_max_f32_e32 v122, v122, v123
	v_max_f32_e32 v124, v206, v206
	v_sub_f32_e32 v123, v122, v206
	v_max_f32_e32 v122, v124, v122
	v_sub_f32_e32 v124, v206, v122
	v_mul_f32_e32 v124, 0x3dd53b94, v124
	v_exp_f32_e32 v124, v124
	s_waitcnt lgkmcnt(0)
	v_mfma_scale_f32_32x32x64_f8f6f4 v[34:49], v[138:145], v[146:153], v[34:49], v1, v1 op_sel_hi:[0,0,0]
	v_cmp_ge_f32_e32 vcc, s61, v123
	s_cmp_eq_u64 vcc, exec
	s_cselect_b64 s[8:9], -1, 0
	s_barrier
	s_waitcnt vmcnt(3)
	v_cndmask_b32_e64 v129, v124, 1.0, s[8:9]
	v_cmp_gt_f32_e32 vcc, 1.0, v129
	s_waitcnt vmcnt(2)
	ds_write_b128 v193, v[164:167] offset:8192
	s_waitcnt vmcnt(1)
	ds_write_b128 v195, v[168:171] offset:28672
	s_waitcnt vmcnt(0)
	ds_write_b64 v197, v[174:175] offset:28672
	v_mfma_scale_f32_32x32x64_f8f6f4 v[18:33], v[138:145], v[210:217], v[18:33], v1, v1 op_sel_hi:[0,0,0]
	s_cbranch_vccz .LBB0_704
	s_and_saveexec_b64 s[58:59], s[6:7]
	ds_write_b32 v185, v129 offset:41088
	s_or_b64 exec, exec, s[58:59]
	s_waitcnt lgkmcnt(0)
	v_add_u32_e32 v123, v183, v184
	ds_read_b128 v[124:127], v123 offset:41184
	ds_read_b128 v[130:133], v123 offset:41152
	ds_read_b128 v[134:137], v123 offset:41120
	ds_read_b128 v[138:141], v123 offset:41088
	s_waitcnt lgkmcnt(3)
	v_pk_mul_f32 v[14:15], v[14:15], v[124:125]
	s_waitcnt lgkmcnt(2)
	v_pk_mul_f32 v[10:11], v[10:11], v[130:131]
	s_waitcnt lgkmcnt(1)
	v_pk_mul_f32 v[6:7], v[6:7], v[134:135]
	v_pk_mul_f32 v[16:17], v[16:17], v[126:127]
	v_pk_mul_f32 v[12:13], v[12:13], v[132:133]
	v_pk_mul_f32 v[8:9], v[8:9], v[136:137]
	s_waitcnt lgkmcnt(0)
	v_pk_mul_f32 v[4:5], v[4:5], v[140:141]
	v_pk_mul_f32 v[2:3], v[2:3], v[138:139]
	v_pk_mul_f32 v[62:63], v[62:63], v[124:125]
	v_pk_mul_f32 v[58:59], v[58:59], v[130:131]
	v_pk_mul_f32 v[54:55], v[54:55], v[134:135]
	v_pk_mul_f32 v[64:65], v[64:65], v[126:127]
	v_pk_mul_f32 v[60:61], v[60:61], v[132:133]
	v_pk_mul_f32 v[56:57], v[56:57], v[136:137]
	v_pk_mul_f32 v[52:53], v[52:53], v[140:141]
	v_pk_mul_f32 v[50:51], v[50:51], v[138:139]
	v_pk_mul_f32 v[46:47], v[46:47], v[124:125]
	v_pk_mul_f32 v[42:43], v[42:43], v[130:131]
	v_pk_mul_f32 v[38:39], v[38:39], v[134:135]
	v_pk_mul_f32 v[48:49], v[48:49], v[126:127]
	v_pk_mul_f32 v[44:45], v[44:45], v[132:133]
	v_pk_mul_f32 v[40:41], v[40:41], v[136:137]
	v_pk_mul_f32 v[36:37], v[36:37], v[140:141]
	v_pk_mul_f32 v[34:35], v[34:35], v[138:139]
	v_pk_mul_f32 v[30:31], v[30:31], v[124:125]
	v_pk_mul_f32 v[26:27], v[26:27], v[130:131]
	v_pk_mul_f32 v[22:23], v[22:23], v[134:135]
	v_pk_mul_f32 v[32:33], v[32:33], v[126:127]
	v_pk_mul_f32 v[28:29], v[28:29], v[132:133]
	v_pk_mul_f32 v[24:25], v[24:25], v[136:137]
	v_pk_mul_f32 v[20:21], v[20:21], v[140:141]
	v_pk_mul_f32 v[18:19], v[18:19], v[138:139]
